# one static priority raise per phase for waves 4-7 (second virtual block), per-segment s_setprio toggling in the GEMM K-loops removed
# baseline (speedup 1.0000x reference)
.LBB0_7:
	v_cmp_lt_u32_e32 vcc, 0xff, v0
	s_setprio 0
	s_cbranch_vccz .Lprio_lo
	s_setprio 1
